# selection QK: dependent lo/hi fp8 MFMA pairs separated by three independent MFMAs, accumulating in place (no back-to-back SrcC dependency)
# baseline (speedup 1.0000x reference)
; __device__ __forceinline__ void nsa_unit(const Params& p, int bg, int jq, LAS unsigned char* lds, int wave, int lane, bool build_lut) {
;     ...
;                 bool ok[2];
;                 ok[0] = (selw[(grp * 4 + q4) * 8 + (nb[0] >> 5)] >> (nb[0] & 31)) & 1u;
;                 ok[1] = real1 && ((selw[(grp * 4 + q4) * 8 + (nb[1] >> 5)] >> (nb[1] & 31)) & 1u);
;                 const int bmax = real1 ? max(nb[0], nb[1]) : nb[0];
;                 const bool fast = (tq0g - 64 * bmax - 63) >= 128;
;                 const bool fresh = m < -1e29f;
;                 const float mref = fresh ? 0.f : m;
;                 float ini[2];
;                 ini[0] = fast ? (ok[0] ? -(mref - lutfar16 - 6.0f) : NEG_INF) : 0.f;
;                 ini[1] = fast ? (ok[1] ? -(mref - lutfar16 - 6.0f) : NEG_INF) : 0.f;
;                 f32x4 sc[2][4];
; #pragma unroll
;                 for (int u = 0; u < 2; ++u)
; #pragma unroll
;                     for (int kt = 0; kt < 4; ++kt) {
;                         sc[u][kt] = __builtin_amdgcn_mfma_f32_16x16x32_fp8_fp8(k8[u][2 * kt], q8[0], (f32x4){ini[u], ini[u], ini[u], ini[u]}, 0, 0, 0);
;                         sc[u][kt] = __builtin_amdgcn_mfma_f32_16x16x32_fp8_fp8(k8[u][2 * kt + 1], q8[1], sc[u][kt], 0, 0, 0);
;                     }
;                 if (it + 1 < npair) {
;                     n0 = __builtin_amdgcn_readfirstlane(list[lbase + 2 * it + 2]); n1 = __builtin_amdgcn_readfirstlane(list[lbase + 2 * it + 3]);
; #pragma unroll
;                     for (int i = 0; i < 4; ++i) { const l64x2 t0 = *(const l64x2*)(ks8 + (size_t)n0 * 4096 + i * 1024 + lane * 16), t1 = *(const l64x2*)(ks8 + (size_t)n1 * 4096 + i * 1024 + lane * 16);
;                         k8[0][2 * i] = t0[0]; k8[0][2 * i + 1] = t0[1]; k8[1][2 * i] = t1[0]; k8[1][2 * i + 1] = t1[1]; }
;                 }
.LBB0_1202:
	s_max_i32 s6, s22, s8
	s_and_b64 s[4:5], s[4:5], exec
	s_cselect_b32 s4, s6, s22
	s_lshl_b32 s4, s4, 6
	s_sub_i32 s4, s39, s4
	s_cmpk_lt_i32 s4, 0xbf
	s_cselect_b64 s[24:25], -1, 0
	s_cmpk_gt_i32 s4, 0xbe
	v_cmp_ngt_f32_e64 s[4:5], s93, v157
	s_waitcnt lgkmcnt(0)
	v_lshrrev_b32_e32 v1, s22, v1
	v_and_b32_e32 v1, 1, v1
	v_cndmask_b32_e64 v156, 0, v157, s[4:5]
	v_sub_f32_e32 v2, v156, v161
	v_add_f32_e32 v2, 0xc0c00000, v2
	v_cmp_eq_u32_e64 s[6:7], 1, v1
	s_cselect_b64 vcc, -1, 0
	s_add_i32 s44, s44, 1
	v_cndmask_b32_e64 v1, v230, -v2, s[6:7]
	v_cndmask_b32_e32 v88, 0, v1, vcc
	v_mov_b32_e32 v89, v88
	v_mov_b32_e32 v90, v88
	v_mov_b32_e32 v91, v88
	v_cndmask_b32_e64 v1, v230, -v2, s[20:21]
	v_cndmask_b32_e32 v120, 0, v1, vcc
	s_cmp_ge_u32 s44, s41
	s_mov_b32 s16, s22
	s_mov_b32 s18, s8
	s_cbranch_scc1 .Lqk_last
	v_readfirstlane_b32 s16, v238
	v_readfirstlane_b32 s18, v239
	s_ashr_i32 s17, s16, 31
	s_lshl_b64 s[46:47], s[16:17], 12
	s_ashr_i32 s19, s18, 31
	v_lshl_add_u64 v[2:3], v[148:149], 0, s[46:47]
	s_lshl_b64 s[46:47], s[18:19], 12
	v_lshl_add_u64 v[238:239], v[148:149], 0, s[46:47]
	s_waitcnt vmcnt(8)
	v_mfma_f32_16x16x32_fp8_fp8 v[116:119], v[16:17], v[152:153], v[88:91]
	v_mov_b32_e32 v121, v120
	v_mov_b32_e32 v122, v120
	v_mov_b32_e32 v123, v120
	v_mfma_f32_16x16x32_fp8_fp8 v[108:111], v[28:29], v[152:153], v[88:91]
	v_mfma_f32_16x16x32_fp8_fp8 v[96:99], v[20:21], v[152:153], v[88:91]
	v_mfma_f32_16x16x32_fp8_fp8 v[100:103], v[36:37], v[152:153], v[88:91]
	v_mfma_f32_16x16x32_fp8_fp8 v[116:119], v[18:19], v[154:155], v[116:119]
	global_load_dwordx4 v[16:19], v[2:3], off
	v_mfma_f32_16x16x32_fp8_fp8 v[108:111], v[30:31], v[154:155], v[108:111]
	global_load_dwordx4 v[28:31], v[2:3], off offset:1024
	v_mfma_f32_16x16x32_fp8_fp8 v[96:99], v[22:23], v[154:155], v[96:99]
	global_load_dwordx4 v[20:23], v[2:3], off offset:2048
	v_mfma_f32_16x16x32_fp8_fp8 v[100:103], v[38:39], v[154:155], v[100:103]
	global_load_dwordx4 v[36:39], v[2:3], off offset:3072
	v_mfma_f32_16x16x32_fp8_fp8 v[112:115], v[4:5], v[152:153], v[120:123]
	v_mfma_f32_16x16x32_fp8_fp8 v[104:107], v[12:13], v[152:153], v[120:123]
	v_mfma_f32_16x16x32_fp8_fp8 v[92:95], v[8:9], v[152:153], v[120:123]
	v_mfma_f32_16x16x32_fp8_fp8 v[88:91], v[32:33], v[152:153], v[120:123]
	v_mfma_f32_16x16x32_fp8_fp8 v[112:115], v[6:7], v[154:155], v[112:115]
	global_load_dwordx4 v[4:7], v[238:239], off
	v_mfma_f32_16x16x32_fp8_fp8 v[104:107], v[14:15], v[154:155], v[104:107]
	global_load_dwordx4 v[12:15], v[238:239], off offset:1024
	v_mfma_f32_16x16x32_fp8_fp8 v[92:95], v[10:11], v[154:155], v[92:95]
	global_load_dwordx4 v[8:11], v[238:239], off offset:2048
	v_mfma_f32_16x16x32_fp8_fp8 v[88:91], v[34:35], v[154:155], v[88:91]
	global_load_dwordx4 v[32:35], v[238:239], off offset:3072
	s_branch .LBB0_1204
.Lqk_last:
	s_waitcnt vmcnt(8)
	v_mfma_f32_16x16x32_fp8_fp8 v[116:119], v[16:17], v[152:153], v[88:91]
	v_mov_b32_e32 v121, v120
	v_mov_b32_e32 v122, v120
	v_mov_b32_e32 v123, v120
	v_mfma_f32_16x16x32_fp8_fp8 v[108:111], v[28:29], v[152:153], v[88:91]
	v_mfma_f32_16x16x32_fp8_fp8 v[96:99], v[20:21], v[152:153], v[88:91]
	v_mfma_f32_16x16x32_fp8_fp8 v[100:103], v[36:37], v[152:153], v[88:91]
	v_mfma_f32_16x16x32_fp8_fp8 v[116:119], v[18:19], v[154:155], v[116:119]
	v_mfma_f32_16x16x32_fp8_fp8 v[108:111], v[30:31], v[154:155], v[108:111]
	v_mfma_f32_16x16x32_fp8_fp8 v[96:99], v[22:23], v[154:155], v[96:99]
	v_mfma_f32_16x16x32_fp8_fp8 v[100:103], v[38:39], v[154:155], v[100:103]
	v_mfma_f32_16x16x32_fp8_fp8 v[112:115], v[4:5], v[152:153], v[120:123]
	v_mfma_f32_16x16x32_fp8_fp8 v[104:107], v[12:13], v[152:153], v[120:123]
	v_mfma_f32_16x16x32_fp8_fp8 v[92:95], v[8:9], v[152:153], v[120:123]
	v_mfma_f32_16x16x32_fp8_fp8 v[88:91], v[32:33], v[152:153], v[120:123]
	v_mfma_f32_16x16x32_fp8_fp8 v[112:115], v[6:7], v[154:155], v[112:115]
	v_mfma_f32_16x16x32_fp8_fp8 v[104:107], v[14:15], v[154:155], v[104:107]
	v_mfma_f32_16x16x32_fp8_fp8 v[92:95], v[10:11], v[154:155], v[92:95]
	v_mfma_f32_16x16x32_fp8_fp8 v[88:91], v[34:35], v[154:155], v[88:91]
